# in-proj and gate/up K-loops with no VALU address arithmetic left: scalar-base LDS-DMA loads plus LDS read offsets folded onto one base register
# speedup vs baseline: 1.0040x; 1.0009x over previous
; #define PG8_STAGE(bufoff, gbase, voff) do { _Pragma("unroll") for (int _i = 0; _i < 2; ++_i) \
;         __builtin_amdgcn_global_load_lds((const unsigned*)((const char*)(gbase) + (voff)[_i]), (PG8_LAS unsigned*)(lds + (bufoff) + ldsw + _i * 8192), 16, 0, 0); } while (0)
; #define PG8_LDA(dst, b, h) do { _Pragma("unroll") for (int m = 0; m < 4; ++m) _Pragma("unroll") for (int k = 0; k < 2; ++k) dst[m][k] = *(const PG8_LAS bf16x8*)(lds + PG8_SA(b, h) + aoff + m * 2048 + k * 1024); } while (0)
; #define PG8_LDB(dst, b, h) do { _Pragma("unroll") for (int n = 0; n < 2; ++n) _Pragma("unroll") for (int k = 0; k < 2; ++k) dst[n][k] = *(const PG8_LAS bf16x8*)(lds + PG8_SB(b, h) + boff + n * 2048 + k * 1024); } while (0)
; #define PG8_MMA(ai, bj, At, Bt) do { __builtin_amdgcn_s_setprio(1); _Pragma("unroll") for (int m = 0; m < 4; ++m) _Pragma("unroll") for (int n = 0; n < 2; ++n) _Pragma("unroll") for (int k = 0; k < 2; ++k) \
;         acc[ai][bj][m][n] = __builtin_amdgcn_mfma_f32_16x16x32_bf16(Bt[n][k], At[m][k], acc[ai][bj][m][n], 0, 0, 0); __builtin_amdgcn_s_setprio(0); } while (0)
; #define PG8_WAIT_V(n) asm volatile("s_waitcnt vmcnt(" #n ")" ::: "memory")
; #define PG8_WAIT_L(n) asm volatile("s_waitcnt lgkmcnt(" #n ")" ::: "memory")
; #define PG8_BAR __builtin_amdgcn_s_barrier()
; #define PG8_SCHED __builtin_amdgcn_sched_barrier(0)
; template <class Epi, class Sched, bool ALIGN_EPI = false, bool SP2 = false>
; __device__ __forceinline__ void gemm_phase(PG8_LAS unsigned char* lds, const Gemm g, const Sched& S, const Epi& E) {
;     ...
;             PG8_LDB(B0, 0, 0); PG8_LDB(B1, 0, 1); PG8_SCHED; PG8_LDA(At, 0, 0); PG8_STAGE(PG8_SA(1, 1), a1 + hstep, voffA);
;             PG8_WAIT_V(8); PG8_WAIT_L(0); PG8_BAR; PG8_MMA(0, 0, At, B0); PG8_MMA(0, 1, At, B1); PG8_BAR; PG8_SCHED;
;             PG8_LDA(At, 0, 1); PG8_STAGE(PG8_SB(0, 0), b2, voffB); PG8_STAGE(PG8_SB(0, 1), b2 + hstep, voffB); PG8_STAGE(PG8_SA(0, 0), a2, voffA);
;             PG8_WAIT_V(8); PG8_WAIT_L(0); PG8_BAR; PG8_MMA(1, 0, At, B0); PG8_MMA(1, 1, At, B1); PG8_BAR; PG8_SCHED;
.LBB0_310:
	s_add_u32 s20, s44, 0xfff80080
	s_addc_u32 s21, s45, -1
	s_add_i32 s30, 0, 0x10000
	s_cmp_eq_u32 s56, 28
	s_cselect_b32 s47, s27, s21
	s_cselect_b32 s46, s52, s20
	s_cselect_b32 s21, s25, s55
	s_cselect_b32 s20, s53, s54
	s_add_i32 s57, 0, 0x14000
	ds_read_b128 v[142:145], v252
	ds_read_b128 v[150:153], v252 offset:1024
	ds_read_b128 v[154:157], v252 offset:2048
	ds_read_b128 v[158:161], v252 offset:3072
	ds_read_b128 v[162:165], v252 offset:16384
	ds_read_b128 v[166:169], v252 offset:17408
	ds_read_b128 v[170:173], v252 offset:18432
	ds_read_b128 v[174:177], v252 offset:19456
	s_add_i32 m0, s12, 0xc000
	ds_read_b128 v[178:181], v148
	ds_read_b128 v[182:185], v148 offset:1024
	ds_read_b128 v[186:189], v148 offset:2048
	ds_read_b128 v[190:193], v148 offset:3072
	ds_read_b128 v[194:197], v148 offset:4096
	ds_read_b128 v[198:201], v148 offset:5120
	ds_read_b128 v[202:205], v148 offset:6144
	ds_read_b128 v[206:209], v148 offset:7168
	global_load_lds_dwordx4 v140, s[44:45]
	s_add_i32 m0, s12, 0xe000
	s_nop 0
	global_load_lds_dwordx4 v138, s[44:45]
	s_waitcnt vmcnt(8)
	s_waitcnt lgkmcnt(0)
	s_barrier
	s_setprio 1
	s_waitcnt lgkmcnt(0)
	v_mfma_f32_16x16x32_bf16 v[128:131], v[142:145], v[178:181], v[128:131]
	v_mfma_f32_16x16x32_bf16 v[124:127], v[154:157], v[178:181], v[124:127]
	v_mfma_f32_16x16x32_bf16 v[120:123], v[142:145], v[186:189], v[120:123]
	v_mfma_f32_16x16x32_bf16 v[112:115], v[154:157], v[186:189], v[112:115]
	v_mfma_f32_16x16x32_bf16 v[104:107], v[142:145], v[194:197], v[104:107]
	v_mfma_f32_16x16x32_bf16 v[96:99], v[154:157], v[194:197], v[96:99]
	v_mfma_f32_16x16x32_bf16 v[88:91], v[142:145], v[202:205], v[88:91]
	v_mfma_f32_16x16x32_bf16 v[80:83], v[154:157], v[202:205], v[80:83]
	v_mfma_f32_16x16x32_bf16 v[128:131], v[150:153], v[182:185], v[128:131]
	v_mfma_f32_16x16x32_bf16 v[124:127], v[158:161], v[182:185], v[124:127]
	v_mfma_f32_16x16x32_bf16 v[120:123], v[150:153], v[190:193], v[120:123]
	v_mfma_f32_16x16x32_bf16 v[112:115], v[158:161], v[190:193], v[112:115]
	v_mfma_f32_16x16x32_bf16 v[104:107], v[150:153], v[198:201], v[104:107]
	v_mfma_f32_16x16x32_bf16 v[96:99], v[158:161], v[198:201], v[96:99]
	v_mfma_f32_16x16x32_bf16 v[88:91], v[150:153], v[206:209], v[88:91]
	v_mfma_f32_16x16x32_bf16 v[80:83], v[158:161], v[206:209], v[80:83]
	s_setprio 0
	s_setprio 1
	v_mfma_f32_16x16x32_bf16 v[116:119], v[162:165], v[178:181], v[116:119]
	v_mfma_f32_16x16x32_bf16 v[108:111], v[170:173], v[178:181], v[108:111]
	v_mfma_f32_16x16x32_bf16 v[100:103], v[162:165], v[186:189], v[100:103]
	v_mfma_f32_16x16x32_bf16 v[92:95], v[170:173], v[186:189], v[92:95]
	v_mfma_f32_16x16x32_bf16 v[84:87], v[162:165], v[194:197], v[84:87]
	v_mfma_f32_16x16x32_bf16 v[76:79], v[170:173], v[194:197], v[76:79]
	v_mfma_f32_16x16x32_bf16 v[72:75], v[162:165], v[202:205], v[72:75]
	v_mfma_f32_16x16x32_bf16 v[68:71], v[170:173], v[202:205], v[68:71]
	v_mfma_f32_16x16x32_bf16 v[116:119], v[166:169], v[182:185], v[116:119]
	v_mfma_f32_16x16x32_bf16 v[108:111], v[174:177], v[182:185], v[108:111]
	v_mfma_f32_16x16x32_bf16 v[100:103], v[166:169], v[190:193], v[100:103]
	v_mfma_f32_16x16x32_bf16 v[92:95], v[174:177], v[190:193], v[92:95]
	v_mfma_f32_16x16x32_bf16 v[84:87], v[166:169], v[198:201], v[84:87]
	v_mfma_f32_16x16x32_bf16 v[76:79], v[174:177], v[198:201], v[76:79]
	v_mfma_f32_16x16x32_bf16 v[72:75], v[166:169], v[206:209], v[72:75]
	v_mfma_f32_16x16x32_bf16 v[68:71], v[174:177], v[206:209], v[68:71]
	s_setprio 0
	s_barrier
	s_add_i32 s30, s30, s10
	s_mov_b32 m0, s30
	ds_read_b128 v[178:181], v148 offset:16384
	ds_read_b128 v[182:185], v148 offset:17408
	ds_read_b128 v[186:189], v148 offset:18432
	ds_read_b128 v[190:193], v148 offset:19456
	ds_read_b128 v[194:197], v148 offset:20480
	ds_read_b128 v[198:201], v148 offset:21504
	ds_read_b128 v[202:205], v148 offset:22528
	ds_read_b128 v[206:209], v148 offset:23552
	global_load_lds_dwordx4 v2, s[20:21]
	s_add_i32 m0, s30, 0x2000
	s_add_u32 s30, s20, 0x80000
	s_addc_u32 s31, s21, 0
	s_add_u32 s98, s20, s28
	s_addc_u32 s99, s21, s29
	s_add_u32 s94, s46, s28
	s_addc_u32 s95, s47, s29
	s_add_i32 s57, s57, s10
	global_load_lds_dwordx4 v132, s[20:21]
	s_mov_b32 m0, s57
	s_nop 0
	global_load_lds_dwordx4 v2, s[30:31]
	s_add_i32 m0, s57, 0x2000
	s_nop 0
	global_load_lds_dwordx4 v132, s[30:31]
	s_mov_b32 m0, s12
	s_nop 0
	global_load_lds_dwordx4 v136, s[46:47]
	s_mov_b32 m0, s13
	s_nop 0
	global_load_lds_dwordx4 v134, s[46:47]
	s_waitcnt vmcnt(8)
	s_waitcnt lgkmcnt(0)
	s_barrier
	s_setprio 1
	s_waitcnt lgkmcnt(0)
	v_mfma_f32_16x16x32_bf16 v[64:67], v[142:145], v[178:181], v[64:67]
	v_mfma_f32_16x16x32_bf16 v[60:63], v[154:157], v[178:181], v[60:63]
	v_mfma_f32_16x16x32_bf16 v[56:59], v[142:145], v[186:189], v[56:59]
	v_mfma_f32_16x16x32_bf16 v[48:51], v[154:157], v[186:189], v[48:51]
	v_mfma_f32_16x16x32_bf16 v[40:43], v[142:145], v[194:197], v[40:43]
	v_mfma_f32_16x16x32_bf16 v[32:35], v[154:157], v[194:197], v[32:35]
	v_mfma_f32_16x16x32_bf16 v[24:27], v[142:145], v[202:205], v[24:27]
	v_mfma_f32_16x16x32_bf16 v[16:19], v[154:157], v[202:205], v[16:19]
	v_mfma_f32_16x16x32_bf16 v[64:67], v[150:153], v[182:185], v[64:67]
	v_mfma_f32_16x16x32_bf16 v[60:63], v[158:161], v[182:185], v[60:63]
	v_mfma_f32_16x16x32_bf16 v[56:59], v[150:153], v[190:193], v[56:59]
	v_mfma_f32_16x16x32_bf16 v[48:51], v[158:161], v[190:193], v[48:51]
	v_mfma_f32_16x16x32_bf16 v[40:43], v[150:153], v[198:201], v[40:43]
	v_mfma_f32_16x16x32_bf16 v[32:35], v[158:161], v[198:201], v[32:35]
	v_mfma_f32_16x16x32_bf16 v[24:27], v[150:153], v[206:209], v[24:27]
	v_mfma_f32_16x16x32_bf16 v[16:19], v[158:161], v[206:209], v[16:19]
	s_setprio 0
	s_setprio 1
	v_mfma_f32_16x16x32_bf16 v[52:55], v[162:165], v[178:181], v[52:55]
	v_mfma_f32_16x16x32_bf16 v[44:47], v[170:173], v[178:181], v[44:47]
	v_mfma_f32_16x16x32_bf16 v[36:39], v[162:165], v[186:189], v[36:39]
	v_mfma_f32_16x16x32_bf16 v[28:31], v[170:173], v[186:189], v[28:31]
	v_mfma_f32_16x16x32_bf16 v[20:23], v[162:165], v[194:197], v[20:23]
	v_mfma_f32_16x16x32_bf16 v[12:15], v[170:173], v[194:197], v[12:15]
	v_mfma_f32_16x16x32_bf16 v[8:11], v[162:165], v[202:205], v[8:11]
	v_mfma_f32_16x16x32_bf16 v[4:7], v[170:173], v[202:205], v[4:7]
	v_mfma_f32_16x16x32_bf16 v[52:55], v[166:169], v[182:185], v[52:55]
	v_mfma_f32_16x16x32_bf16 v[44:47], v[174:177], v[182:185], v[44:47]
	v_mfma_f32_16x16x32_bf16 v[36:39], v[166:169], v[190:193], v[36:39]
	v_mfma_f32_16x16x32_bf16 v[28:31], v[174:177], v[190:193], v[28:31]
	v_mfma_f32_16x16x32_bf16 v[20:23], v[166:169], v[198:201], v[20:23]
	v_mfma_f32_16x16x32_bf16 v[12:15], v[174:177], v[198:201], v[12:15]
	v_mfma_f32_16x16x32_bf16 v[8:11], v[166:169], v[206:209], v[8:11]
	v_mfma_f32_16x16x32_bf16 v[4:7], v[174:177], v[206:209], v[4:7]
	s_setprio 0
	s_barrier
; #define PG8_STAGE(bufoff, gbase, voff) do { _Pragma("unroll") for (int _i = 0; _i < 2; ++_i) \
;         __builtin_amdgcn_global_load_lds((const unsigned*)((const char*)(gbase) + (voff)[_i]), (PG8_LAS unsigned*)(lds + (bufoff) + ldsw + _i * 8192), 16, 0, 0); } while (0)
; #define PG8_LDA(dst, b, h) do { _Pragma("unroll") for (int m = 0; m < 4; ++m) _Pragma("unroll") for (int k = 0; k < 2; ++k) dst[m][k] = *(const PG8_LAS bf16x8*)(lds + PG8_SA(b, h) + aoff + m * 2048 + k * 1024); } while (0)
; #define PG8_LDB(dst, b, h) do { _Pragma("unroll") for (int n = 0; n < 2; ++n) _Pragma("unroll") for (int k = 0; k < 2; ++k) dst[n][k] = *(const PG8_LAS bf16x8*)(lds + PG8_SB(b, h) + boff + n * 2048 + k * 1024); } while (0)
; #define PG8_MMA(ai, bj, At, Bt) do { __builtin_amdgcn_s_setprio(1); _Pragma("unroll") for (int m = 0; m < 4; ++m) _Pragma("unroll") for (int n = 0; n < 2; ++n) _Pragma("unroll") for (int k = 0; k < 2; ++k) \
;         acc[ai][bj][m][n] = __builtin_amdgcn_mfma_f32_16x16x32_bf16(Bt[n][k], At[m][k], acc[ai][bj][m][n], 0, 0, 0); __builtin_amdgcn_s_setprio(0); } while (0)
; #define PG8_WAIT_V(n) asm volatile("s_waitcnt vmcnt(" #n ")" ::: "memory")
; #define PG8_WAIT_L(n) asm volatile("s_waitcnt lgkmcnt(" #n ")" ::: "memory")
; #define PG8_BAR __builtin_amdgcn_s_barrier()
; #define PG8_SCHED __builtin_amdgcn_sched_barrier(0)
; template <class Epi, class Sched, bool ALIGN_EPI = false, bool SP2 = false>
; __device__ __forceinline__ void gemm_phase(PG8_LAS unsigned char* lds, const Gemm g, const Sched& S, const Epi& E) {
;     ...
;             PG8_LDB(B0, 1, 0); PG8_LDB(B1, 1, 1); PG8_SCHED; PG8_LDA(At, 1, 0); PG8_STAGE(PG8_SA(0, 1), a2 + hstep, voffA);
;             PG8_WAIT_V(8); PG8_WAIT_L(0); PG8_BAR; PG8_MMA(0, 0, At, B0); PG8_MMA(0, 1, At, B1); PG8_BAR; PG8_SCHED;
;             PG8_LDA(At, 1, 1); PG8_STAGE(PG8_SB(1, 0), b3, voffB); PG8_STAGE(PG8_SB(1, 1), b3 + hstep, voffB); PG8_STAGE(PG8_SA(1, 0), a3, voffA);
;             PG8_WAIT_V(8); PG8_WAIT_L(0); PG8_BAR; PG8_MMA(1, 0, At, B0); PG8_MMA(1, 1, At, B1); PG8_BAR; PG8_SCHED;
	s_add_i32 s57, 0, 0x18000
	s_add_i32 s58, 0, 0x1c000
	ds_read_b128 v[142:145], v252 offset:32768
	ds_read_b128 v[150:153], v252 offset:33792
	ds_read_b128 v[154:157], v252 offset:34816
	ds_read_b128 v[158:161], v252 offset:35840
	ds_read_b128 v[162:165], v252 offset:49152
	ds_read_b128 v[166:169], v252 offset:50176
	ds_read_b128 v[170:173], v252 offset:51200
	ds_read_b128 v[174:177], v252 offset:52224
	s_add_u32 s30, s46, 0x80000
	s_addc_u32 s31, s47, 0
	s_mov_b32 m0, s33
	ds_read_b128 v[178:181], v148 offset:32768
	ds_read_b128 v[182:185], v148 offset:33792
	ds_read_b128 v[186:189], v148 offset:34816
	ds_read_b128 v[190:193], v148 offset:35840
	ds_read_b128 v[194:197], v148 offset:36864
	ds_read_b128 v[198:201], v148 offset:37888
	ds_read_b128 v[202:205], v148 offset:38912
	ds_read_b128 v[206:209], v148 offset:39936
	global_load_lds_dwordx4 v136, s[30:31]
	s_mov_b32 m0, s37
	s_nop 0
	global_load_lds_dwordx4 v134, s[30:31]
	s_waitcnt vmcnt(8)
	s_waitcnt lgkmcnt(0)
	s_barrier
	s_setprio 1
	s_waitcnt lgkmcnt(0)
	v_mfma_f32_16x16x32_bf16 v[128:131], v[142:145], v[178:181], v[128:131]
	v_mfma_f32_16x16x32_bf16 v[124:127], v[154:157], v[178:181], v[124:127]
	v_mfma_f32_16x16x32_bf16 v[120:123], v[142:145], v[186:189], v[120:123]
	v_mfma_f32_16x16x32_bf16 v[112:115], v[154:157], v[186:189], v[112:115]
	v_mfma_f32_16x16x32_bf16 v[104:107], v[142:145], v[194:197], v[104:107]
	v_mfma_f32_16x16x32_bf16 v[96:99], v[154:157], v[194:197], v[96:99]
	v_mfma_f32_16x16x32_bf16 v[88:91], v[142:145], v[202:205], v[88:91]
	v_mfma_f32_16x16x32_bf16 v[80:83], v[154:157], v[202:205], v[80:83]
	v_mfma_f32_16x16x32_bf16 v[128:131], v[150:153], v[182:185], v[128:131]
	v_mfma_f32_16x16x32_bf16 v[124:127], v[158:161], v[182:185], v[124:127]
	v_mfma_f32_16x16x32_bf16 v[120:123], v[150:153], v[190:193], v[120:123]
	v_mfma_f32_16x16x32_bf16 v[112:115], v[158:161], v[190:193], v[112:115]
	v_mfma_f32_16x16x32_bf16 v[104:107], v[150:153], v[198:201], v[104:107]
	v_mfma_f32_16x16x32_bf16 v[96:99], v[158:161], v[198:201], v[96:99]
	v_mfma_f32_16x16x32_bf16 v[88:91], v[150:153], v[206:209], v[88:91]
	v_mfma_f32_16x16x32_bf16 v[80:83], v[158:161], v[206:209], v[80:83]
	s_setprio 0
	s_setprio 1
	v_mfma_f32_16x16x32_bf16 v[116:119], v[162:165], v[178:181], v[116:119]
	v_mfma_f32_16x16x32_bf16 v[108:111], v[170:173], v[178:181], v[108:111]
	v_mfma_f32_16x16x32_bf16 v[100:103], v[162:165], v[186:189], v[100:103]
	v_mfma_f32_16x16x32_bf16 v[92:95], v[170:173], v[186:189], v[92:95]
	v_mfma_f32_16x16x32_bf16 v[84:87], v[162:165], v[194:197], v[84:87]
	v_mfma_f32_16x16x32_bf16 v[76:79], v[170:173], v[194:197], v[76:79]
	v_mfma_f32_16x16x32_bf16 v[72:75], v[162:165], v[202:205], v[72:75]
	v_mfma_f32_16x16x32_bf16 v[68:71], v[170:173], v[202:205], v[68:71]
	v_mfma_f32_16x16x32_bf16 v[116:119], v[166:169], v[182:185], v[116:119]
	v_mfma_f32_16x16x32_bf16 v[108:111], v[174:177], v[182:185], v[108:111]
	v_mfma_f32_16x16x32_bf16 v[100:103], v[166:169], v[190:193], v[100:103]
	v_mfma_f32_16x16x32_bf16 v[92:95], v[174:177], v[190:193], v[92:95]
	v_mfma_f32_16x16x32_bf16 v[84:87], v[166:169], v[198:201], v[84:87]
	v_mfma_f32_16x16x32_bf16 v[76:79], v[174:177], v[198:201], v[76:79]
	v_mfma_f32_16x16x32_bf16 v[72:75], v[166:169], v[206:209], v[72:75]
	v_mfma_f32_16x16x32_bf16 v[68:71], v[174:177], v[206:209], v[68:71]
	s_setprio 0
	s_barrier
	s_add_i32 s30, s57, s10
	s_mov_b32 m0, s30
	ds_read_b128 v[178:181], v148 offset:49152
	ds_read_b128 v[182:185], v148 offset:50176
	ds_read_b128 v[186:189], v148 offset:51200
	ds_read_b128 v[190:193], v148 offset:52224
	ds_read_b128 v[194:197], v148 offset:53248
	ds_read_b128 v[198:201], v148 offset:54272
	ds_read_b128 v[202:205], v148 offset:55296
	ds_read_b128 v[206:209], v148 offset:56320
	global_load_lds_dwordx4 v2, s[98:99]
	s_add_i32 m0, s30, 0x2000
	s_add_u32 s20, s20, 0x80080
	s_addc_u32 s21, s21, 0
	s_add_i32 s30, s58, s10
	global_load_lds_dwordx4 v132, s[98:99]
	s_mov_b32 m0, s30
	s_nop 0
	global_load_lds_dwordx4 v2, s[20:21]
	s_add_i32 m0, s30, 0x2000
	s_nop 0
	global_load_lds_dwordx4 v132, s[20:21]
	s_mov_b32 m0, s18
	s_nop 0
	global_load_lds_dwordx4 v136, s[94:95]
	s_mov_b32 m0, s48
	s_nop 0
	global_load_lds_dwordx4 v134, s[94:95]
	s_waitcnt vmcnt(8)
	s_waitcnt lgkmcnt(0)
	s_barrier
	s_setprio 1
	s_waitcnt lgkmcnt(0)
	v_mfma_f32_16x16x32_bf16 v[64:67], v[142:145], v[178:181], v[64:67]
	v_mfma_f32_16x16x32_bf16 v[60:63], v[154:157], v[178:181], v[60:63]
	v_mfma_f32_16x16x32_bf16 v[56:59], v[142:145], v[186:189], v[56:59]
	v_mfma_f32_16x16x32_bf16 v[48:51], v[154:157], v[186:189], v[48:51]
	v_mfma_f32_16x16x32_bf16 v[40:43], v[142:145], v[194:197], v[40:43]
	v_mfma_f32_16x16x32_bf16 v[32:35], v[154:157], v[194:197], v[32:35]
	v_mfma_f32_16x16x32_bf16 v[24:27], v[142:145], v[202:205], v[24:27]
	v_mfma_f32_16x16x32_bf16 v[16:19], v[154:157], v[202:205], v[16:19]
	v_mfma_f32_16x16x32_bf16 v[64:67], v[150:153], v[182:185], v[64:67]
	v_mfma_f32_16x16x32_bf16 v[60:63], v[158:161], v[182:185], v[60:63]
	v_mfma_f32_16x16x32_bf16 v[56:59], v[150:153], v[190:193], v[56:59]
	v_mfma_f32_16x16x32_bf16 v[48:51], v[158:161], v[190:193], v[48:51]
	v_mfma_f32_16x16x32_bf16 v[40:43], v[150:153], v[198:201], v[40:43]
	v_mfma_f32_16x16x32_bf16 v[32:35], v[158:161], v[198:201], v[32:35]
	v_mfma_f32_16x16x32_bf16 v[24:27], v[150:153], v[206:209], v[24:27]
	v_mfma_f32_16x16x32_bf16 v[16:19], v[158:161], v[206:209], v[16:19]
	s_setprio 0
	s_setprio 1
	v_mfma_f32_16x16x32_bf16 v[52:55], v[162:165], v[178:181], v[52:55]
	v_mfma_f32_16x16x32_bf16 v[44:47], v[170:173], v[178:181], v[44:47]
	v_mfma_f32_16x16x32_bf16 v[36:39], v[162:165], v[186:189], v[36:39]
	v_mfma_f32_16x16x32_bf16 v[28:31], v[170:173], v[186:189], v[28:31]
	v_mfma_f32_16x16x32_bf16 v[20:23], v[162:165], v[194:197], v[20:23]
	v_mfma_f32_16x16x32_bf16 v[12:15], v[170:173], v[194:197], v[12:15]
	v_mfma_f32_16x16x32_bf16 v[8:11], v[162:165], v[202:205], v[8:11]
	v_mfma_f32_16x16x32_bf16 v[4:7], v[170:173], v[202:205], v[4:7]
	v_mfma_f32_16x16x32_bf16 v[52:55], v[166:169], v[182:185], v[52:55]
	v_mfma_f32_16x16x32_bf16 v[44:47], v[174:177], v[182:185], v[44:47]
	v_mfma_f32_16x16x32_bf16 v[36:39], v[166:169], v[190:193], v[36:39]
	v_mfma_f32_16x16x32_bf16 v[28:31], v[174:177], v[190:193], v[28:31]
	v_mfma_f32_16x16x32_bf16 v[20:23], v[166:169], v[198:201], v[20:23]
	v_mfma_f32_16x16x32_bf16 v[12:15], v[174:177], v[198:201], v[12:15]
	v_mfma_f32_16x16x32_bf16 v[8:11], v[166:169], v[206:209], v[8:11]
	v_mfma_f32_16x16x32_bf16 v[4:7], v[174:177], v[206:209], v[4:7]
	s_setprio 0
	s_barrier
	s_add_i32 s56, s56, 2
	s_add_u32 s54, s54, 0x100
	s_addc_u32 s55, s55, 0
	s_add_u32 s44, s44, 0x100
	s_addc_u32 s45, s45, 0
	s_cmp_gt_u32 s56, 29
	s_cbranch_scc0 .LBB0_310
	s_and_b64 vcc, exec, s[22:23]
	s_cbranch_vccz .LBB0_313
	s_barrier

; #define PG8_STAGE(bufoff, gbase, voff) do { _Pragma("unroll") for (int _i = 0; _i < 2; ++_i) \
;         __builtin_amdgcn_global_load_lds((const unsigned*)((const char*)(gbase) + (voff)[_i]), (PG8_LAS unsigned*)(lds + (bufoff) + ldsw + _i * 8192), 16, 0, 0); } while (0)
; #define PG8_LDA(dst, b, h) do { _Pragma("unroll") for (int m = 0; m < 4; ++m) _Pragma("unroll") for (int k = 0; k < 2; ++k) dst[m][k] = *(const PG8_LAS bf16x8*)(lds + PG8_SA(b, h) + aoff + m * 2048 + k * 1024); } while (0)
; #define PG8_LDB(dst, b, h) do { _Pragma("unroll") for (int n = 0; n < 2; ++n) _Pragma("unroll") for (int k = 0; k < 2; ++k) dst[n][k] = *(const PG8_LAS bf16x8*)(lds + PG8_SB(b, h) + boff + n * 2048 + k * 1024); } while (0)
; #define PG8_MMA(ai, bj, At, Bt) do { __builtin_amdgcn_s_setprio(1); _Pragma("unroll") for (int m = 0; m < 4; ++m) _Pragma("unroll") for (int n = 0; n < 2; ++n) _Pragma("unroll") for (int k = 0; k < 2; ++k) \
;         acc[ai][bj][m][n] = __builtin_amdgcn_mfma_f32_16x16x32_bf16(Bt[n][k], At[m][k], acc[ai][bj][m][n], 0, 0, 0); __builtin_amdgcn_s_setprio(0); } while (0)
; #define PG8_WAIT_V(n) asm volatile("s_waitcnt vmcnt(" #n ")" ::: "memory")
; #define PG8_WAIT_L(n) asm volatile("s_waitcnt lgkmcnt(" #n ")" ::: "memory")
; #define PG8_BAR __builtin_amdgcn_s_barrier()
; #define PG8_SCHED __builtin_amdgcn_sched_barrier(0)
; template <class Epi, class Sched, bool ALIGN_EPI = false, bool SP2 = false>
; __device__ __forceinline__ void gemm_phase(PG8_LAS unsigned char* lds, const Gemm g, const Sched& S, const Epi& E) {
;     ...
;             PG8_LDB(B0, 0, 0); PG8_LDB(B1, 0, 1); PG8_SCHED; PG8_LDA(At, 0, 0); PG8_STAGE(PG8_SA(1, 1), a1 + hstep, voffA);
;             PG8_WAIT_V(8); PG8_WAIT_L(0); PG8_BAR; PG8_MMA(0, 0, At, B0); PG8_MMA(0, 1, At, B1); PG8_BAR; PG8_SCHED;
;             PG8_LDA(At, 0, 1); PG8_STAGE(PG8_SB(0, 0), b2, voffB); PG8_STAGE(PG8_SB(0, 1), b2 + hstep, voffB); PG8_STAGE(PG8_SA(0, 0), a2, voffA);
;             PG8_WAIT_V(8); PG8_WAIT_L(0); PG8_BAR; PG8_MMA(1, 0, At, B0); PG8_MMA(1, 1, At, B1); PG8_BAR; PG8_SCHED;
.LBB0_2165:
	s_add_u32 s20, s44, 0xfff80080
	s_addc_u32 s21, s45, -1
	s_add_i32 s30, 0, 0x10000
	s_cmp_eq_u32 s56, 28
	s_cselect_b32 s47, s12, s21
	s_cselect_b32 s46, s13, s20
	s_cselect_b32 s21, s25, s55
	s_cselect_b32 s20, s27, s33
	s_add_i32 s57, 0, 0x14000
	ds_read_b128 v[142:145], v252
	ds_read_b128 v[150:153], v252 offset:1024
	ds_read_b128 v[154:157], v252 offset:2048
	ds_read_b128 v[158:161], v252 offset:3072
	ds_read_b128 v[162:165], v252 offset:16384
	ds_read_b128 v[166:169], v252 offset:17408
	ds_read_b128 v[170:173], v252 offset:18432
	ds_read_b128 v[174:177], v252 offset:19456
	s_add_i32 m0, s43, 0xc000
	ds_read_b128 v[178:181], v148
	ds_read_b128 v[182:185], v148 offset:1024
	ds_read_b128 v[186:189], v148 offset:2048
	ds_read_b128 v[190:193], v148 offset:3072
	ds_read_b128 v[194:197], v148 offset:4096
	ds_read_b128 v[198:201], v148 offset:5120
	ds_read_b128 v[202:205], v148 offset:6144
	ds_read_b128 v[206:209], v148 offset:7168
	global_load_lds_dwordx4 v140, s[44:45]
	s_add_i32 m0, s43, 0xe000
	s_nop 0
	global_load_lds_dwordx4 v138, s[44:45]
	s_waitcnt vmcnt(8)
	s_waitcnt lgkmcnt(0)
	s_barrier
	s_setprio 1
	s_waitcnt lgkmcnt(0)
	v_mfma_f32_16x16x32_bf16 v[128:131], v[142:145], v[178:181], v[128:131]
	v_mfma_f32_16x16x32_bf16 v[120:123], v[154:157], v[178:181], v[120:123]
	v_mfma_f32_16x16x32_bf16 v[112:115], v[142:145], v[186:189], v[112:115]
	v_mfma_f32_16x16x32_bf16 v[104:107], v[154:157], v[186:189], v[104:107]
	v_mfma_f32_16x16x32_bf16 v[96:99], v[142:145], v[194:197], v[96:99]
	v_mfma_f32_16x16x32_bf16 v[88:91], v[154:157], v[194:197], v[88:91]
	v_mfma_f32_16x16x32_bf16 v[80:83], v[142:145], v[202:205], v[80:83]
	v_mfma_f32_16x16x32_bf16 v[72:75], v[154:157], v[202:205], v[72:75]
	v_mfma_f32_16x16x32_bf16 v[128:131], v[150:153], v[182:185], v[128:131]
	v_mfma_f32_16x16x32_bf16 v[120:123], v[158:161], v[182:185], v[120:123]
	v_mfma_f32_16x16x32_bf16 v[112:115], v[150:153], v[190:193], v[112:115]
	v_mfma_f32_16x16x32_bf16 v[104:107], v[158:161], v[190:193], v[104:107]
	v_mfma_f32_16x16x32_bf16 v[96:99], v[150:153], v[198:201], v[96:99]
	v_mfma_f32_16x16x32_bf16 v[88:91], v[158:161], v[198:201], v[88:91]
	v_mfma_f32_16x16x32_bf16 v[80:83], v[150:153], v[206:209], v[80:83]
	v_mfma_f32_16x16x32_bf16 v[72:75], v[158:161], v[206:209], v[72:75]
	s_setprio 0
	s_setprio 1
	v_mfma_f32_16x16x32_bf16 v[124:127], v[162:165], v[178:181], v[124:127]
	v_mfma_f32_16x16x32_bf16 v[116:119], v[170:173], v[178:181], v[116:119]
	v_mfma_f32_16x16x32_bf16 v[108:111], v[162:165], v[186:189], v[108:111]
	v_mfma_f32_16x16x32_bf16 v[100:103], v[170:173], v[186:189], v[100:103]
	v_mfma_f32_16x16x32_bf16 v[92:95], v[162:165], v[194:197], v[92:95]
	v_mfma_f32_16x16x32_bf16 v[84:87], v[170:173], v[194:197], v[84:87]
	v_mfma_f32_16x16x32_bf16 v[76:79], v[162:165], v[202:205], v[76:79]
	v_mfma_f32_16x16x32_bf16 v[68:71], v[170:173], v[202:205], v[68:71]
	v_mfma_f32_16x16x32_bf16 v[124:127], v[166:169], v[182:185], v[124:127]
	v_mfma_f32_16x16x32_bf16 v[116:119], v[174:177], v[182:185], v[116:119]
	v_mfma_f32_16x16x32_bf16 v[108:111], v[166:169], v[190:193], v[108:111]
	v_mfma_f32_16x16x32_bf16 v[100:103], v[174:177], v[190:193], v[100:103]
	v_mfma_f32_16x16x32_bf16 v[92:95], v[166:169], v[198:201], v[92:95]
	v_mfma_f32_16x16x32_bf16 v[84:87], v[174:177], v[198:201], v[84:87]
	v_mfma_f32_16x16x32_bf16 v[76:79], v[166:169], v[206:209], v[76:79]
	v_mfma_f32_16x16x32_bf16 v[68:71], v[174:177], v[206:209], v[68:71]
	s_setprio 0
	s_barrier
	s_add_i32 s30, s30, s11
	s_mov_b32 m0, s30
	ds_read_b128 v[178:181], v148 offset:16384
	ds_read_b128 v[182:185], v148 offset:17408
	ds_read_b128 v[186:189], v148 offset:18432
	ds_read_b128 v[190:193], v148 offset:19456
	ds_read_b128 v[194:197], v148 offset:20480
	ds_read_b128 v[198:201], v148 offset:21504
	ds_read_b128 v[202:205], v148 offset:22528
	ds_read_b128 v[206:209], v148 offset:23552
	global_load_lds_dwordx4 v2, s[20:21]
	s_add_i32 m0, s30, 0x2000
	s_add_u32 s30, s20, 0x80000
	s_addc_u32 s31, s21, 0
	s_add_u32 s98, s20, s28
	s_addc_u32 s99, s21, s29
	s_add_u32 s94, s46, s28
	s_addc_u32 s95, s47, s29
	s_add_i32 s57, s57, s11
	global_load_lds_dwordx4 v132, s[20:21]
	s_mov_b32 m0, s57
	s_nop 0
	global_load_lds_dwordx4 v2, s[30:31]
	s_add_i32 m0, s57, 0x2000
	s_nop 0
	global_load_lds_dwordx4 v132, s[30:31]
	s_mov_b32 m0, s43
	s_nop 0
	global_load_lds_dwordx4 v136, s[46:47]
	s_mov_b32 m0, s49
	s_nop 0
	global_load_lds_dwordx4 v134, s[46:47]
	s_waitcnt vmcnt(8)
	s_waitcnt lgkmcnt(0)
	s_barrier
	s_setprio 1
	s_waitcnt lgkmcnt(0)
	v_mfma_f32_16x16x32_bf16 v[64:67], v[142:145], v[178:181], v[64:67]
	v_mfma_f32_16x16x32_bf16 v[56:59], v[154:157], v[178:181], v[56:59]
	v_mfma_f32_16x16x32_bf16 v[48:51], v[142:145], v[186:189], v[48:51]
	v_mfma_f32_16x16x32_bf16 v[40:43], v[154:157], v[186:189], v[40:43]
	v_mfma_f32_16x16x32_bf16 v[32:35], v[142:145], v[194:197], v[32:35]
	v_mfma_f32_16x16x32_bf16 v[24:27], v[154:157], v[194:197], v[24:27]
	v_mfma_f32_16x16x32_bf16 v[16:19], v[142:145], v[202:205], v[16:19]
	v_mfma_f32_16x16x32_bf16 v[8:11], v[154:157], v[202:205], v[8:11]
	v_mfma_f32_16x16x32_bf16 v[64:67], v[150:153], v[182:185], v[64:67]
	v_mfma_f32_16x16x32_bf16 v[56:59], v[158:161], v[182:185], v[56:59]
	v_mfma_f32_16x16x32_bf16 v[48:51], v[150:153], v[190:193], v[48:51]
	v_mfma_f32_16x16x32_bf16 v[40:43], v[158:161], v[190:193], v[40:43]
	v_mfma_f32_16x16x32_bf16 v[32:35], v[150:153], v[198:201], v[32:35]
	v_mfma_f32_16x16x32_bf16 v[24:27], v[158:161], v[198:201], v[24:27]
	v_mfma_f32_16x16x32_bf16 v[16:19], v[150:153], v[206:209], v[16:19]
	v_mfma_f32_16x16x32_bf16 v[8:11], v[158:161], v[206:209], v[8:11]
	s_setprio 0
	s_setprio 1
	v_mfma_f32_16x16x32_bf16 v[60:63], v[162:165], v[178:181], v[60:63]
	v_mfma_f32_16x16x32_bf16 v[52:55], v[170:173], v[178:181], v[52:55]
	v_mfma_f32_16x16x32_bf16 v[44:47], v[162:165], v[186:189], v[44:47]
	v_mfma_f32_16x16x32_bf16 v[36:39], v[170:173], v[186:189], v[36:39]
	v_mfma_f32_16x16x32_bf16 v[28:31], v[162:165], v[194:197], v[28:31]
	v_mfma_f32_16x16x32_bf16 v[20:23], v[170:173], v[194:197], v[20:23]
	v_mfma_f32_16x16x32_bf16 v[12:15], v[162:165], v[202:205], v[12:15]
	v_mfma_f32_16x16x32_bf16 v[4:7], v[170:173], v[202:205], v[4:7]
	v_mfma_f32_16x16x32_bf16 v[60:63], v[166:169], v[182:185], v[60:63]
	v_mfma_f32_16x16x32_bf16 v[52:55], v[174:177], v[182:185], v[52:55]
	v_mfma_f32_16x16x32_bf16 v[44:47], v[166:169], v[190:193], v[44:47]
	v_mfma_f32_16x16x32_bf16 v[36:39], v[174:177], v[190:193], v[36:39]
	v_mfma_f32_16x16x32_bf16 v[28:31], v[166:169], v[198:201], v[28:31]
	v_mfma_f32_16x16x32_bf16 v[20:23], v[174:177], v[198:201], v[20:23]
	v_mfma_f32_16x16x32_bf16 v[12:15], v[166:169], v[206:209], v[12:15]
	v_mfma_f32_16x16x32_bf16 v[4:7], v[174:177], v[206:209], v[4:7]
	s_setprio 0
	s_barrier
; #define PG8_STAGE(bufoff, gbase, voff) do { _Pragma("unroll") for (int _i = 0; _i < 2; ++_i) \
;         __builtin_amdgcn_global_load_lds((const unsigned*)((const char*)(gbase) + (voff)[_i]), (PG8_LAS unsigned*)(lds + (bufoff) + ldsw + _i * 8192), 16, 0, 0); } while (0)
; #define PG8_LDA(dst, b, h) do { _Pragma("unroll") for (int m = 0; m < 4; ++m) _Pragma("unroll") for (int k = 0; k < 2; ++k) dst[m][k] = *(const PG8_LAS bf16x8*)(lds + PG8_SA(b, h) + aoff + m * 2048 + k * 1024); } while (0)
; #define PG8_LDB(dst, b, h) do { _Pragma("unroll") for (int n = 0; n < 2; ++n) _Pragma("unroll") for (int k = 0; k < 2; ++k) dst[n][k] = *(const PG8_LAS bf16x8*)(lds + PG8_SB(b, h) + boff + n * 2048 + k * 1024); } while (0)
; #define PG8_MMA(ai, bj, At, Bt) do { __builtin_amdgcn_s_setprio(1); _Pragma("unroll") for (int m = 0; m < 4; ++m) _Pragma("unroll") for (int n = 0; n < 2; ++n) _Pragma("unroll") for (int k = 0; k < 2; ++k) \
;         acc[ai][bj][m][n] = __builtin_amdgcn_mfma_f32_16x16x32_bf16(Bt[n][k], At[m][k], acc[ai][bj][m][n], 0, 0, 0); __builtin_amdgcn_s_setprio(0); } while (0)
; #define PG8_WAIT_V(n) asm volatile("s_waitcnt vmcnt(" #n ")" ::: "memory")
; #define PG8_WAIT_L(n) asm volatile("s_waitcnt lgkmcnt(" #n ")" ::: "memory")
; #define PG8_BAR __builtin_amdgcn_s_barrier()
; #define PG8_SCHED __builtin_amdgcn_sched_barrier(0)
; template <class Epi, class Sched, bool ALIGN_EPI = false, bool SP2 = false>
; __device__ __forceinline__ void gemm_phase(PG8_LAS unsigned char* lds, const Gemm g, const Sched& S, const Epi& E) {
;     ...
;             PG8_LDB(B0, 1, 0); PG8_LDB(B1, 1, 1); PG8_SCHED; PG8_LDA(At, 1, 0); PG8_STAGE(PG8_SA(0, 1), a2 + hstep, voffA);
;             PG8_WAIT_V(8); PG8_WAIT_L(0); PG8_BAR; PG8_MMA(0, 0, At, B0); PG8_MMA(0, 1, At, B1); PG8_BAR; PG8_SCHED;
;             PG8_LDA(At, 1, 1); PG8_STAGE(PG8_SB(1, 0), b3, voffB); PG8_STAGE(PG8_SB(1, 1), b3 + hstep, voffB); PG8_STAGE(PG8_SA(1, 0), a3, voffA);
;             PG8_WAIT_V(8); PG8_WAIT_L(0); PG8_BAR; PG8_MMA(1, 0, At, B0); PG8_MMA(1, 1, At, B1); PG8_BAR; PG8_SCHED;
	s_add_i32 s57, 0, 0x18000
	s_add_i32 s58, 0, 0x1c000
	ds_read_b128 v[142:145], v252 offset:32768
	ds_read_b128 v[150:153], v252 offset:33792
	ds_read_b128 v[154:157], v252 offset:34816
	ds_read_b128 v[158:161], v252 offset:35840
	ds_read_b128 v[162:165], v252 offset:49152
	ds_read_b128 v[166:169], v252 offset:50176
	ds_read_b128 v[170:173], v252 offset:51200
	ds_read_b128 v[174:177], v252 offset:52224
	s_add_u32 s30, s46, 0x80000
	s_addc_u32 s31, s47, 0
	s_mov_b32 m0, s50
	ds_read_b128 v[178:181], v148 offset:32768
	ds_read_b128 v[182:185], v148 offset:33792
	ds_read_b128 v[186:189], v148 offset:34816
	ds_read_b128 v[190:193], v148 offset:35840
	ds_read_b128 v[194:197], v148 offset:36864
	ds_read_b128 v[198:201], v148 offset:37888
	ds_read_b128 v[202:205], v148 offset:38912
	ds_read_b128 v[206:209], v148 offset:39936
	global_load_lds_dwordx4 v136, s[30:31]
	s_mov_b32 m0, s51
	s_nop 0
	global_load_lds_dwordx4 v134, s[30:31]
	s_waitcnt vmcnt(8)
	s_waitcnt lgkmcnt(0)
	s_barrier
	s_setprio 1
	s_waitcnt lgkmcnt(0)
	v_mfma_f32_16x16x32_bf16 v[128:131], v[142:145], v[178:181], v[128:131]
	v_mfma_f32_16x16x32_bf16 v[120:123], v[154:157], v[178:181], v[120:123]
	v_mfma_f32_16x16x32_bf16 v[112:115], v[142:145], v[186:189], v[112:115]
	v_mfma_f32_16x16x32_bf16 v[104:107], v[154:157], v[186:189], v[104:107]
	v_mfma_f32_16x16x32_bf16 v[96:99], v[142:145], v[194:197], v[96:99]
	v_mfma_f32_16x16x32_bf16 v[88:91], v[154:157], v[194:197], v[88:91]
	v_mfma_f32_16x16x32_bf16 v[80:83], v[142:145], v[202:205], v[80:83]
	v_mfma_f32_16x16x32_bf16 v[72:75], v[154:157], v[202:205], v[72:75]
	v_mfma_f32_16x16x32_bf16 v[128:131], v[150:153], v[182:185], v[128:131]
	v_mfma_f32_16x16x32_bf16 v[120:123], v[158:161], v[182:185], v[120:123]
	v_mfma_f32_16x16x32_bf16 v[112:115], v[150:153], v[190:193], v[112:115]
	v_mfma_f32_16x16x32_bf16 v[104:107], v[158:161], v[190:193], v[104:107]
	v_mfma_f32_16x16x32_bf16 v[96:99], v[150:153], v[198:201], v[96:99]
	v_mfma_f32_16x16x32_bf16 v[88:91], v[158:161], v[198:201], v[88:91]
	v_mfma_f32_16x16x32_bf16 v[80:83], v[150:153], v[206:209], v[80:83]
	v_mfma_f32_16x16x32_bf16 v[72:75], v[158:161], v[206:209], v[72:75]
	s_setprio 0
	s_setprio 1
	v_mfma_f32_16x16x32_bf16 v[124:127], v[162:165], v[178:181], v[124:127]
	v_mfma_f32_16x16x32_bf16 v[116:119], v[170:173], v[178:181], v[116:119]
	v_mfma_f32_16x16x32_bf16 v[108:111], v[162:165], v[186:189], v[108:111]
	v_mfma_f32_16x16x32_bf16 v[100:103], v[170:173], v[186:189], v[100:103]
	v_mfma_f32_16x16x32_bf16 v[92:95], v[162:165], v[194:197], v[92:95]
	v_mfma_f32_16x16x32_bf16 v[84:87], v[170:173], v[194:197], v[84:87]
	v_mfma_f32_16x16x32_bf16 v[76:79], v[162:165], v[202:205], v[76:79]
	v_mfma_f32_16x16x32_bf16 v[68:71], v[170:173], v[202:205], v[68:71]
	v_mfma_f32_16x16x32_bf16 v[124:127], v[166:169], v[182:185], v[124:127]
	v_mfma_f32_16x16x32_bf16 v[116:119], v[174:177], v[182:185], v[116:119]
	v_mfma_f32_16x16x32_bf16 v[108:111], v[166:169], v[190:193], v[108:111]
	v_mfma_f32_16x16x32_bf16 v[100:103], v[174:177], v[190:193], v[100:103]
	v_mfma_f32_16x16x32_bf16 v[92:95], v[166:169], v[198:201], v[92:95]
	v_mfma_f32_16x16x32_bf16 v[84:87], v[174:177], v[198:201], v[84:87]
	v_mfma_f32_16x16x32_bf16 v[76:79], v[166:169], v[206:209], v[76:79]
	v_mfma_f32_16x16x32_bf16 v[68:71], v[174:177], v[206:209], v[68:71]
	s_setprio 0
	s_barrier
	s_add_i32 s30, s57, s11
	s_mov_b32 m0, s30
	ds_read_b128 v[178:181], v148 offset:49152
	ds_read_b128 v[182:185], v148 offset:50176
	ds_read_b128 v[186:189], v148 offset:51200
	ds_read_b128 v[190:193], v148 offset:52224
	ds_read_b128 v[194:197], v148 offset:53248
	ds_read_b128 v[198:201], v148 offset:54272
	ds_read_b128 v[202:205], v148 offset:55296
	ds_read_b128 v[206:209], v148 offset:56320
	global_load_lds_dwordx4 v2, s[98:99]
	s_add_i32 m0, s30, 0x2000
	s_add_u32 s20, s20, 0x80080
	s_addc_u32 s21, s21, 0
	s_add_i32 s30, s58, s11
	global_load_lds_dwordx4 v132, s[98:99]
	s_mov_b32 m0, s30
	s_nop 0
	global_load_lds_dwordx4 v2, s[20:21]
	s_add_i32 m0, s30, 0x2000
	s_nop 0
	global_load_lds_dwordx4 v132, s[20:21]
	s_mov_b32 m0, s18
	s_nop 0
	global_load_lds_dwordx4 v136, s[94:95]
	s_mov_b32 m0, s52
	s_nop 0
	global_load_lds_dwordx4 v134, s[94:95]
	s_waitcnt vmcnt(8)
	s_waitcnt lgkmcnt(0)
	s_barrier
	s_setprio 1
	s_waitcnt lgkmcnt(0)
	v_mfma_f32_16x16x32_bf16 v[64:67], v[142:145], v[178:181], v[64:67]
	v_mfma_f32_16x16x32_bf16 v[56:59], v[154:157], v[178:181], v[56:59]
	v_mfma_f32_16x16x32_bf16 v[48:51], v[142:145], v[186:189], v[48:51]
	v_mfma_f32_16x16x32_bf16 v[40:43], v[154:157], v[186:189], v[40:43]
	v_mfma_f32_16x16x32_bf16 v[32:35], v[142:145], v[194:197], v[32:35]
	v_mfma_f32_16x16x32_bf16 v[24:27], v[154:157], v[194:197], v[24:27]
	v_mfma_f32_16x16x32_bf16 v[16:19], v[142:145], v[202:205], v[16:19]
	v_mfma_f32_16x16x32_bf16 v[8:11], v[154:157], v[202:205], v[8:11]
	v_mfma_f32_16x16x32_bf16 v[64:67], v[150:153], v[182:185], v[64:67]
	v_mfma_f32_16x16x32_bf16 v[56:59], v[158:161], v[182:185], v[56:59]
	v_mfma_f32_16x16x32_bf16 v[48:51], v[150:153], v[190:193], v[48:51]
	v_mfma_f32_16x16x32_bf16 v[40:43], v[158:161], v[190:193], v[40:43]
	v_mfma_f32_16x16x32_bf16 v[32:35], v[150:153], v[198:201], v[32:35]
	v_mfma_f32_16x16x32_bf16 v[24:27], v[158:161], v[198:201], v[24:27]
	v_mfma_f32_16x16x32_bf16 v[16:19], v[150:153], v[206:209], v[16:19]
	v_mfma_f32_16x16x32_bf16 v[8:11], v[158:161], v[206:209], v[8:11]
	s_setprio 0
	s_setprio 1
	v_mfma_f32_16x16x32_bf16 v[60:63], v[162:165], v[178:181], v[60:63]
	v_mfma_f32_16x16x32_bf16 v[52:55], v[170:173], v[178:181], v[52:55]
	v_mfma_f32_16x16x32_bf16 v[44:47], v[162:165], v[186:189], v[44:47]
	v_mfma_f32_16x16x32_bf16 v[36:39], v[170:173], v[186:189], v[36:39]
	v_mfma_f32_16x16x32_bf16 v[28:31], v[162:165], v[194:197], v[28:31]
	v_mfma_f32_16x16x32_bf16 v[20:23], v[170:173], v[194:197], v[20:23]
	v_mfma_f32_16x16x32_bf16 v[12:15], v[162:165], v[202:205], v[12:15]
	v_mfma_f32_16x16x32_bf16 v[4:7], v[170:173], v[202:205], v[4:7]
	v_mfma_f32_16x16x32_bf16 v[60:63], v[166:169], v[182:185], v[60:63]
	v_mfma_f32_16x16x32_bf16 v[52:55], v[174:177], v[182:185], v[52:55]
	v_mfma_f32_16x16x32_bf16 v[44:47], v[166:169], v[190:193], v[44:47]
	v_mfma_f32_16x16x32_bf16 v[36:39], v[174:177], v[190:193], v[36:39]
	v_mfma_f32_16x16x32_bf16 v[28:31], v[166:169], v[198:201], v[28:31]
	v_mfma_f32_16x16x32_bf16 v[20:23], v[174:177], v[198:201], v[20:23]
	v_mfma_f32_16x16x32_bf16 v[12:15], v[166:169], v[206:209], v[12:15]
	v_mfma_f32_16x16x32_bf16 v[4:7], v[174:177], v[206:209], v[4:7]
	s_setprio 0
	s_barrier
	s_add_i32 s56, s56, 2
	s_add_u32 s33, s33, 0x100
	s_addc_u32 s55, s55, 0
	s_add_u32 s44, s44, 0x100
	s_addc_u32 s45, s45, 0
	s_cmp_gt_u32 s56, 29
	s_cbranch_scc0 .LBB0_2165
	s_and_b64 vcc, exec, s[22:23]
	s_cbranch_vccz .LBB0_2168
	s_barrier
